# v25 + DFT stage 2: the 16 tile-invariant twiddle-fragment loads hoisted out of the tile loop into spare VGPRs (16 of 48 VMEM instructions per tile per wave removed)
# speedup vs baseline: 1.0120x; 1.0120x over previous
.LBB0_114:
	s_cbranch_execz .LBB0_111
	v_readlane_b32 s2, v247, 39
	v_readlane_b32 s3, v247, 40
	s_andn2_b64 vcc, exec, s[2:3]
	s_cbranch_vccnz .LBB0_118
	v_lshrrev_b32_e32 v1, 5, v201
	v_lshl_or_b32 v2, s23, 1, v1
	v_and_b32_e32 v1, 15, v200
	v_lshl_or_b32 v4, s23, 4, v1
	v_ashrrev_i32_e32 v5, 31, v4
	v_readlane_b32 s8, v245, 20
	v_lshrrev_b32_e32 v1, 2, v200
	v_lshlrev_b64 v[6:7], 9, v[4:5]
	v_readlane_b32 s9, v245, 21
	v_and_b32_e32 v8, 12, v1
	v_lshlrev_b32_e32 v154, 1, v8
	v_lshl_add_u64 v[6:7], s[8:9], 0, v[6:7]
	v_lshrrev_b32_e32 v1, 2, v201
	v_lshlrev_b32_e32 v3, 3, v201
	s_and_b64 s[2:3], s[76:77], exec
	v_lshl_add_u64 v[6:7], v[6:7], 0, v[154:155]
	s_mov_b64 s[8:9], 0x2aa0000
	v_mul_u32_u24_e32 v1, 0x120, v1
	v_and_b32_e32 v3, 24, v3
	v_lshl_add_u64 v[34:35], v[6:7], 0, s[8:9]
	s_cselect_b32 s8, 4, 6
	v_add3_u32 v91, 0, v1, v3
	v_ashrrev_i32_e32 v3, 31, v2
	v_lshlrev_b64 v[36:37], s8, v[4:5]
	v_lshlrev_b64 v[38:39], 11, v[2:3]
	s_mov_b64 s[8:9], 0x8000
	v_lshl_add_u64 v[40:41], v[38:39], 0, s[8:9]
	s_mov_b64 s[8:9], 0x10000
	v_lshl_add_u64 v[42:43], v[38:39], 0, s[8:9]
	s_mov_b64 s[8:9], 0x18000
	v_lshl_add_u64 v[44:45], v[38:39], 0, s[8:9]
	s_mov_b64 s[8:9], 0x20000
	v_lshl_add_u64 v[46:47], v[38:39], 0, s[8:9]
	s_mov_b64 s[8:9], 0x28000
	v_lshl_add_u64 v[48:49], v[38:39], 0, s[8:9]
	s_mov_b64 s[8:9], 0x30000
	v_lshl_add_u64 v[50:51], v[38:39], 0, s[8:9]
	s_mov_b64 s[8:9], 0x38000
	v_lshl_add_u64 v[52:53], v[38:39], 0, s[8:9]
	s_mov_b64 s[8:9], 0x40000
	v_lshl_add_u64 v[54:55], v[38:39], 0, s[8:9]
	s_mov_b64 s[8:9], 0x48000
	v_lshl_add_u64 v[56:57], v[38:39], 0, s[8:9]
	s_mov_b64 s[8:9], 0x50000
	v_lshl_add_u64 v[58:59], v[38:39], 0, s[8:9]
	s_mov_b64 s[8:9], 0x58000
	v_lshl_add_u64 v[60:61], v[38:39], 0, s[8:9]
	s_mov_b64 s[8:9], 0x60000
	v_lshl_add_u64 v[62:63], v[38:39], 0, s[8:9]
	s_mov_b64 s[8:9], 0x68000
	v_lshl_add_u64 v[64:65], v[38:39], 0, s[8:9]
	s_mov_b64 s[8:9], 0x70000
	v_lshl_add_u64 v[66:67], v[38:39], 0, s[8:9]
	s_mov_b64 s[8:9], 0x78000
	s_cselect_b32 s2, 16, 64
	v_lshl_add_u64 v[68:69], v[38:39], 0, s[8:9]
	s_movk_i32 s8, 0x120
	v_mul_lo_u32 v100, v2, s8
	v_cvt_f32_ubyte0_e32 v2, s2
	v_rcp_iflag_f32_e32 v2, v2
	v_lshlrev_b32_e32 v0, 2, v200
	s_cselect_b32 s3, 11, 13
	s_sub_i32 s8, 0, s2
	v_mul_f32_e32 v2, 0x4f7ffffe, v2
	v_cvt_u32_f32_e32 v2, v2
	v_and_b32_e32 v0, 0x7c, v0
	v_cndmask_b32_e64 v32, v187, v198, s[76:77]
	v_lshl_add_u32 v90, v0, 1, 0
	v_readfirstlane_b32 s9, v2
	s_mul_i32 s8, s8, s9
	v_add_u32_e32 v1, 0x1200, v100
	s_mul_hi_u32 s8, s9, s8
	v_add_u32_e32 v92, 0x10e00, v91
	v_add_u32_e32 v93, 0x10e20, v91
	v_add_u32_e32 v94, 0x10e40, v91
	v_add_u32_e32 v95, 0x10e60, v91
	v_add_u32_e32 v96, 0x10e80, v91
	v_add_u32_e32 v97, 0x10ea0, v91
	v_add_u32_e32 v98, 0x10ec0, v91
	v_add_u32_e32 v99, 0x10ee0, v91
	v_mov_b32_e32 v33, v32
	s_add_i32 s13, s9, s8
	v_lshlrev_b32_e32 v154, 1, v0
	v_add_u32_e32 v101, v90, v1
	v_lshlrev_b32_e32 v70, 1, v8
	v_readlane_b32 s18, v246, 62
	s_mov_b32 s22, s47
	global_load_dwordx2 v[238:239], v[34:35], off
	global_load_dwordx2 v[240:241], v[34:35], off offset:32
	global_load_dwordx2 v[234:235], v[34:35], off offset:64
	global_load_dwordx2 v[236:237], v[34:35], off offset:96
	global_load_dwordx2 v[230:231], v[34:35], off offset:128
	global_load_dwordx2 v[232:233], v[34:35], off offset:160
	global_load_dwordx2 v[226:227], v[34:35], off offset:192
	global_load_dwordx2 v[228:229], v[34:35], off offset:224
	global_load_dwordx2 v[222:223], v[34:35], off offset:256
	global_load_dwordx2 v[224:225], v[34:35], off offset:288
	global_load_dwordx2 v[218:219], v[34:35], off offset:320
	global_load_dwordx2 v[220:221], v[34:35], off offset:352
	global_load_dwordx2 v[214:215], v[34:35], off offset:384
	global_load_dwordx2 v[216:217], v[34:35], off offset:416
	global_load_dwordx2 v[210:211], v[34:35], off offset:448
	global_load_dwordx2 v[212:213], v[34:35], off offset:480
.LBB0_117:
	s_ashr_i32 s8, s22, 3
	s_abs_i32 s10, s8
	s_mul_hi_u32 s11, s10, s13
	s_mul_i32 s14, s11, s2
	s_sub_i32 s10, s10, s14
	s_ashr_i32 s9, s22, 31
	s_add_i32 s14, s11, 1
	s_sub_i32 s15, s10, s2
	s_cmp_ge_u32 s10, s2
	s_cselect_b32 s11, s14, s11
	s_cselect_b32 s10, s15, s10
	s_add_i32 s14, s11, 1
	s_cmp_ge_u32 s10, s2
	s_cselect_b32 s10, s14, s11
	s_xor_b32 s10, s10, s9
	s_sub_i32 s10, s10, s9
	s_mul_i32 s9, s10, s2
	s_sub_i32 s14, s8, s9
	s_mulk_i32 s8, 0x101
	s_ashr_i32 s9, s8, 31
	s_lshl_b64 s[8:9], s[8:9], 11
	s_add_u32 s11, s4, s8
	s_addc_u32 s15, s5, s9
	s_and_b32 s8, s18, 0x380
	s_lshl_b32 s8, s8, 1
	s_add_u32 s24, s11, s8
	s_addc_u32 s25, s15, 0
	v_lshl_add_u64 v[0:1], s[24:25], 0, v[154:155]
	v_lshl_add_u64 v[2:3], v[0:1], 0, v[38:39]
	global_load_dwordx2 v[72:73], v[2:3], off
	v_lshl_add_u64 v[2:3], v[0:1], 0, v[40:41]
	global_load_dwordx2 v[74:75], v[2:3], off
	v_lshl_add_u64 v[2:3], v[0:1], 0, v[42:43]
	global_load_dwordx2 v[76:77], v[2:3], off
	v_lshl_add_u64 v[2:3], v[0:1], 0, v[44:45]
	global_load_dwordx2 v[78:79], v[2:3], off
	v_lshl_add_u64 v[2:3], v[0:1], 0, v[46:47]
	global_load_dwordx2 v[80:81], v[2:3], off
	v_lshl_add_u64 v[2:3], v[0:1], 0, v[48:49]
	global_load_dwordx2 v[82:83], v[2:3], off
	v_lshl_add_u64 v[2:3], v[0:1], 0, v[50:51]
	global_load_dwordx2 v[84:85], v[2:3], off
	v_lshl_add_u64 v[2:3], v[0:1], 0, v[52:53]
	global_load_dwordx2 v[86:87], v[2:3], off
	v_lshl_add_u64 v[2:3], v[0:1], 0, v[54:55]
	global_load_dwordx2 v[88:89], v[2:3], off
	v_lshl_add_u64 v[2:3], v[0:1], 0, v[56:57]
	global_load_dwordx2 v[102:103], v[2:3], off
	v_lshl_add_u64 v[2:3], v[0:1], 0, v[58:59]
	global_load_dwordx2 v[104:105], v[2:3], off
	v_lshl_add_u64 v[2:3], v[0:1], 0, v[60:61]
	global_load_dwordx2 v[106:107], v[2:3], off
	v_lshl_add_u64 v[2:3], v[0:1], 0, v[62:63]
	global_load_dwordx2 v[108:109], v[2:3], off
	v_lshl_add_u64 v[2:3], v[0:1], 0, v[64:65]
	global_load_dwordx2 v[110:111], v[2:3], off
	v_lshl_add_u64 v[2:3], v[0:1], 0, v[66:67]
	global_load_dwordx2 v[112:113], v[2:3], off
	v_lshl_add_u64 v[0:1], v[0:1], 0, v[68:69]
	global_load_dwordx2 v[114:115], v[0:1], off
	s_ashr_i32 s11, s10, 31
	s_lshl_b64 s[10:11], s[10:11], s3
	s_ashr_i32 s15, s14, 31
	s_add_u32 s10, s10, s14
	v_add_u32_e32 v71, v90, v100
	s_addc_u32 s11, s11, s15
	s_mov_b32 s9, s96
	s_waitcnt vmcnt(14)
	ds_write2st64_b64 v71, v[72:73], v[74:75] offset1:9
	s_waitcnt vmcnt(12)
	ds_write2st64_b64 v71, v[76:77], v[78:79] offset0:18 offset1:27
	s_waitcnt vmcnt(10)
	ds_write2st64_b64 v71, v[80:81], v[82:83] offset0:36 offset1:45
	s_waitcnt vmcnt(8)
	ds_write2st64_b64 v71, v[84:85], v[86:87] offset0:54 offset1:63
	s_waitcnt vmcnt(6)
	ds_write2st64_b64 v71, v[88:89], v[102:103] offset0:72 offset1:81
	s_waitcnt vmcnt(4)
	ds_write2st64_b64 v71, v[104:105], v[106:107] offset0:90 offset1:99
	s_waitcnt vmcnt(2)
	ds_write2st64_b64 v71, v[108:109], v[110:111] offset0:108 offset1:117
	s_waitcnt vmcnt(1)
	ds_write_b64 v71, v[112:113] offset:64512
	s_waitcnt vmcnt(0)
	ds_write_b64 v101, v[114:115] offset:64512
	v_lshl_add_u64 v[72:73], s[10:11], 0, v[36:37]
	v_mov_b64_e32 v[74:75], s[92:93]
	v_mad_u64_u32 v[74:75], s[10:11], v72, s33, v[74:75]
	v_mad_i32_i24 v75, v73, s33, v75
	v_lshl_add_u64 v[74:75], v[74:75], 0, s[8:9]
	v_mov_b32_e32 v71, v155
	v_lshl_add_u64 v[74:75], v[74:75], 0, v[70:71]
	v_lshl_add_u64 v[102:103], v[74:75], 0, s[72:73]
	v_add_co_u32_e32 v74, vcc, s69, v74
	s_waitcnt lgkmcnt(0)
	s_nop 0
	v_addc_co_u32_e32 v75, vcc, 0, v75, vcc
	s_barrier
	global_load_dwordx2 v[88:89], v[74:75], off
	global_load_dwordx2 v[86:87], v[102:103], off offset:32
	global_load_dwordx2 v[84:85], v[102:103], off offset:64
	global_load_dwordx2 v[82:83], v[102:103], off offset:96
	global_load_dwordx2 v[80:81], v[102:103], off offset:128
	global_load_dwordx2 v[78:79], v[102:103], off offset:160
	global_load_dwordx2 v[76:77], v[102:103], off offset:192
	global_load_dwordx2 v[74:75], v[102:103], off offset:224
	ds_read_b64_tr_b16 v[104:105], v91 offset:4608
	ds_read_b64_tr_b16 v[102:103], v91
	ds_read_b64_tr_b16 v[106:107], v91 offset:32
	ds_read_b64_tr_b16 v[108:109], v91 offset:4640
	ds_read_b64_tr_b16 v[110:111], v91 offset:64
	ds_read_b64_tr_b16 v[112:113], v91 offset:4672
	ds_read_b64_tr_b16 v[114:115], v91 offset:96
	ds_read_b64_tr_b16 v[116:117], v91 offset:4704
	ds_read_b64_tr_b16 v[118:119], v91 offset:128
	ds_read_b64_tr_b16 v[120:121], v91 offset:4736
	ds_read_b64_tr_b16 v[122:123], v91 offset:160
	ds_read_b64_tr_b16 v[124:125], v91 offset:4768
	ds_read_b64_tr_b16 v[126:127], v91 offset:192
	ds_read_b64_tr_b16 v[128:129], v91 offset:4800
	ds_read_b64_tr_b16 v[130:131], v91 offset:224
	ds_read_b64_tr_b16 v[132:133], v91 offset:4832
	ds_read_b64_tr_b16 v[134:135], v91 offset:9216
	ds_read_b64_tr_b16 v[136:137], v91 offset:13824
	ds_read_b64_tr_b16 v[138:139], v91 offset:9248
	ds_read_b64_tr_b16 v[140:141], v91 offset:13856
	ds_read_b64_tr_b16 v[142:143], v91 offset:9280
	ds_read_b64_tr_b16 v[144:145], v91 offset:13888
	ds_read_b64_tr_b16 v[146:147], v91 offset:9312
	ds_read_b64_tr_b16 v[148:149], v91 offset:13920
	ds_read_b64_tr_b16 v[156:157], v91 offset:9344
	ds_read_b64_tr_b16 v[158:159], v91 offset:13952
	ds_read_b64_tr_b16 v[160:161], v91 offset:9376
	ds_read_b64_tr_b16 v[162:163], v91 offset:13984
	ds_read_b64_tr_b16 v[164:165], v91 offset:9408
	ds_read_b64_tr_b16 v[166:167], v91 offset:14016
	ds_read_b64_tr_b16 v[168:169], v91 offset:9440
	ds_read_b64_tr_b16 v[170:171], v91 offset:14048
	s_waitcnt vmcnt(22) lgkmcnt(14)
	v_mfma_f32_16x16x32_bf16 v[102:105], v[102:105], v[238:241], 0
	v_mfma_f32_16x16x32_bf16 v[106:109], v[106:109], v[238:241], 0
	v_mfma_f32_16x16x32_bf16 v[110:113], v[110:113], v[238:241], 0
	v_mfma_f32_16x16x32_bf16 v[114:117], v[114:117], v[238:241], 0
	v_mfma_f32_16x16x32_bf16 v[118:121], v[118:121], v[238:241], 0
	v_mfma_f32_16x16x32_bf16 v[122:125], v[122:125], v[238:241], 0
	v_mfma_f32_16x16x32_bf16 v[126:129], v[126:129], v[238:241], 0
	v_mfma_f32_16x16x32_bf16 v[28:31], v[130:133], v[238:241], 0
	ds_read_b64_tr_b16 v[130:131], v91 offset:18432
	ds_read_b64_tr_b16 v[172:173], v91 offset:18464
	ds_read_b64_tr_b16 v[176:177], v91 offset:18496
	ds_read_b64_tr_b16 v[180:181], v91 offset:18528
	ds_read_b64_tr_b16 v[132:133], v91 offset:23040
	ds_read_b64_tr_b16 v[174:175], v91 offset:23072
	ds_read_b64_tr_b16 v[178:179], v91 offset:23104
	ds_read_b64_tr_b16 v[182:183], v91 offset:23136
	ds_read_b64_tr_b16 v[188:189], v91 offset:18560
	ds_read_b64_tr_b16 v[192:193], v91 offset:18592
	ds_read_b64_tr_b16 v[202:203], v91 offset:18624
	ds_read_b64_tr_b16 v[206:207], v91 offset:18656
	ds_read_b64_tr_b16 v[190:191], v91 offset:23168
	ds_read_b64_tr_b16 v[194:195], v91 offset:23200
	ds_read_b64_tr_b16 v[204:205], v91 offset:23232
	ds_read_b64_tr_b16 v[208:209], v91 offset:23264
	s_waitcnt vmcnt(20)
	v_mfma_f32_16x16x32_bf16 v[102:105], v[134:137], v[234:237], v[102:105]
	s_waitcnt lgkmcnt(14)
	v_mfma_f32_16x16x32_bf16 v[106:109], v[138:141], v[234:237], v[106:109]
	v_mfma_f32_16x16x32_bf16 v[110:113], v[142:145], v[234:237], v[110:113]
	v_mfma_f32_16x16x32_bf16 v[114:117], v[146:149], v[234:237], v[114:117]
	v_mfma_f32_16x16x32_bf16 v[118:121], v[156:159], v[234:237], v[118:121]
	v_mfma_f32_16x16x32_bf16 v[122:125], v[160:163], v[234:237], v[122:125]
	v_mfma_f32_16x16x32_bf16 v[126:129], v[164:167], v[234:237], v[126:129]
	v_mfma_f32_16x16x32_bf16 v[24:27], v[168:171], v[234:237], v[28:31]
	s_nop 2
	ds_read_b64_tr_b16 v[28:29], v91 offset:27648
	ds_read_b64_tr_b16 v[134:135], v91 offset:27680
	ds_read_b64_tr_b16 v[138:139], v91 offset:27712
	ds_read_b64_tr_b16 v[142:143], v91 offset:27744
	ds_read_b64_tr_b16 v[30:31], v91 offset:32256
	ds_read_b64_tr_b16 v[136:137], v91 offset:32288
	ds_read_b64_tr_b16 v[140:141], v91 offset:32320
	ds_read_b64_tr_b16 v[144:145], v91 offset:32352
	ds_read_b64_tr_b16 v[146:147], v91 offset:27776
	ds_read_b64_tr_b16 v[156:157], v91 offset:27808
	ds_read_b64_tr_b16 v[160:161], v91 offset:27840
	ds_read_b64_tr_b16 v[164:165], v91 offset:27872
	ds_read_b64_tr_b16 v[148:149], v91 offset:32384
	ds_read_b64_tr_b16 v[158:159], v91 offset:32416
	ds_read_b64_tr_b16 v[162:163], v91 offset:32448
	ds_read_b64_tr_b16 v[166:167], v91 offset:32480
	s_waitcnt vmcnt(18) lgkmcnt(14)
	v_mfma_f32_16x16x32_bf16 v[102:105], v[130:133], v[230:233], v[102:105]
	v_mfma_f32_16x16x32_bf16 v[106:109], v[172:175], v[230:233], v[106:109]
	v_mfma_f32_16x16x32_bf16 v[110:113], v[176:179], v[230:233], v[110:113]
	v_mfma_f32_16x16x32_bf16 v[114:117], v[180:183], v[230:233], v[114:117]
	v_mfma_f32_16x16x32_bf16 v[118:121], v[188:191], v[230:233], v[118:121]
	v_mfma_f32_16x16x32_bf16 v[122:125], v[192:195], v[230:233], v[122:125]
	v_mfma_f32_16x16x32_bf16 v[126:129], v[202:205], v[230:233], v[126:129]
	v_mfma_f32_16x16x32_bf16 v[20:23], v[206:209], v[230:233], v[24:27]
	s_nop 2
	ds_read_b64_tr_b16 v[24:25], v91 offset:36864
	ds_read_b64_tr_b16 v[130:131], v91 offset:36896
	ds_read_b64_tr_b16 v[168:169], v91 offset:36928
	ds_read_b64_tr_b16 v[172:173], v91 offset:36960
	ds_read_b64_tr_b16 v[26:27], v91 offset:41472
	ds_read_b64_tr_b16 v[132:133], v91 offset:41504
	ds_read_b64_tr_b16 v[170:171], v91 offset:41536
	ds_read_b64_tr_b16 v[174:175], v91 offset:41568
	ds_read_b64_tr_b16 v[176:177], v91 offset:36992
	ds_read_b64_tr_b16 v[180:181], v91 offset:37024
	ds_read_b64_tr_b16 v[188:189], v91 offset:37056
	ds_read_b64_tr_b16 v[192:193], v91 offset:37088
	ds_read_b64_tr_b16 v[178:179], v91 offset:41600
	ds_read_b64_tr_b16 v[182:183], v91 offset:41632
	ds_read_b64_tr_b16 v[190:191], v91 offset:41664
	ds_read_b64_tr_b16 v[194:195], v91 offset:41696
	s_waitcnt vmcnt(16) lgkmcnt(14)
	v_mfma_f32_16x16x32_bf16 v[28:31], v[28:31], v[226:229], v[102:105]
	v_mfma_f32_16x16x32_bf16 v[102:105], v[134:137], v[226:229], v[106:109]
	v_mfma_f32_16x16x32_bf16 v[106:109], v[138:141], v[226:229], v[110:113]
	v_mfma_f32_16x16x32_bf16 v[110:113], v[142:145], v[226:229], v[114:117]
	v_mfma_f32_16x16x32_bf16 v[114:117], v[146:149], v[226:229], v[118:121]
	v_mfma_f32_16x16x32_bf16 v[118:121], v[156:159], v[226:229], v[122:125]
	v_mfma_f32_16x16x32_bf16 v[122:125], v[160:163], v[226:229], v[126:129]
	v_mfma_f32_16x16x32_bf16 v[16:19], v[164:167], v[226:229], v[20:23]
	s_nop 2
	ds_read_b64_tr_b16 v[20:21], v91 offset:46080
	ds_read_b64_tr_b16 v[126:127], v91 offset:46112
	ds_read_b64_tr_b16 v[134:135], v91 offset:46144
	ds_read_b64_tr_b16 v[138:139], v91 offset:46176
	ds_read_b64_tr_b16 v[22:23], v91 offset:50688
	ds_read_b64_tr_b16 v[128:129], v91 offset:50720
	ds_read_b64_tr_b16 v[136:137], v91 offset:50752
	ds_read_b64_tr_b16 v[140:141], v91 offset:50784
	ds_read_b64_tr_b16 v[142:143], v91 offset:46208
	ds_read_b64_tr_b16 v[146:147], v91 offset:46240
	ds_read_b64_tr_b16 v[156:157], v91 offset:46272
	ds_read_b64_tr_b16 v[160:161], v91 offset:46304
	ds_read_b64_tr_b16 v[144:145], v91 offset:50816
	ds_read_b64_tr_b16 v[148:149], v91 offset:50848
	ds_read_b64_tr_b16 v[158:159], v91 offset:50880
	ds_read_b64_tr_b16 v[162:163], v91 offset:50912
	s_waitcnt vmcnt(14) lgkmcnt(14)
	v_mfma_f32_16x16x32_bf16 v[24:27], v[24:27], v[222:225], v[28:31]
	v_mfma_f32_16x16x32_bf16 v[28:31], v[130:133], v[222:225], v[102:105]
	v_mfma_f32_16x16x32_bf16 v[102:105], v[168:171], v[222:225], v[106:109]
	v_mfma_f32_16x16x32_bf16 v[106:109], v[172:175], v[222:225], v[110:113]
	v_mfma_f32_16x16x32_bf16 v[110:113], v[176:179], v[222:225], v[114:117]
	v_mfma_f32_16x16x32_bf16 v[114:117], v[180:183], v[222:225], v[118:121]
	v_mfma_f32_16x16x32_bf16 v[118:121], v[188:191], v[222:225], v[122:125]
	v_mfma_f32_16x16x32_bf16 v[12:15], v[192:195], v[222:225], v[16:19]
	s_nop 2
	ds_read_b64_tr_b16 v[16:17], v91 offset:55296
	ds_read_b64_tr_b16 v[122:123], v91 offset:55328
	ds_read_b64_tr_b16 v[130:131], v91 offset:55360
	ds_read_b64_tr_b16 v[164:165], v91 offset:55392
	ds_read_b64_tr_b16 v[18:19], v91 offset:59904
	ds_read_b64_tr_b16 v[124:125], v91 offset:59936
	ds_read_b64_tr_b16 v[132:133], v91 offset:59968
	ds_read_b64_tr_b16 v[166:167], v91 offset:60000
	ds_read_b64_tr_b16 v[168:169], v91 offset:55424
	ds_read_b64_tr_b16 v[172:173], v91 offset:55456
	ds_read_b64_tr_b16 v[176:177], v91 offset:55488
	ds_read_b64_tr_b16 v[180:181], v91 offset:55520
	ds_read_b64_tr_b16 v[170:171], v91 offset:60032
	ds_read_b64_tr_b16 v[174:175], v91 offset:60064
	ds_read_b64_tr_b16 v[178:179], v91 offset:60096
	ds_read_b64_tr_b16 v[182:183], v91 offset:60128
	s_waitcnt vmcnt(12) lgkmcnt(14)
	v_mfma_f32_16x16x32_bf16 v[20:23], v[20:23], v[218:221], v[24:27]
	v_mfma_f32_16x16x32_bf16 v[24:27], v[126:129], v[218:221], v[28:31]
	v_mfma_f32_16x16x32_bf16 v[28:31], v[134:137], v[218:221], v[102:105]
	v_mfma_f32_16x16x32_bf16 v[102:105], v[138:141], v[218:221], v[106:109]
	v_mfma_f32_16x16x32_bf16 v[106:109], v[142:145], v[218:221], v[110:113]
	v_mfma_f32_16x16x32_bf16 v[110:113], v[146:149], v[218:221], v[114:117]
	v_mfma_f32_16x16x32_bf16 v[114:117], v[156:159], v[218:221], v[118:121]
	v_mfma_f32_16x16x32_bf16 v[8:11], v[160:163], v[218:221], v[12:15]
	s_nop 2
	ds_read_b64_tr_b16 v[12:13], v91 offset:64512
	ds_read_b64_tr_b16 v[118:119], v91 offset:64544
	ds_read_b64_tr_b16 v[126:127], v91 offset:64576
	ds_read_b64_tr_b16 v[134:135], v91 offset:64608
	ds_read_b64_tr_b16 v[14:15], v92
	ds_read_b64_tr_b16 v[120:121], v93
	ds_read_b64_tr_b16 v[128:129], v94
	ds_read_b64_tr_b16 v[136:137], v95
	ds_read_b64_tr_b16 v[138:139], v91 offset:64640
	ds_read_b64_tr_b16 v[142:143], v91 offset:64672
	ds_read_b64_tr_b16 v[146:147], v91 offset:64704
	ds_read_b64_tr_b16 v[156:157], v91 offset:64736
	ds_read_b64_tr_b16 v[140:141], v96
	ds_read_b64_tr_b16 v[144:145], v97
	ds_read_b64_tr_b16 v[148:149], v98
	ds_read_b64_tr_b16 v[158:159], v99
	s_waitcnt vmcnt(10) lgkmcnt(14)
	v_mfma_f32_16x16x32_bf16 v[16:19], v[16:19], v[214:217], v[20:23]
	v_mfma_f32_16x16x32_bf16 v[20:23], v[122:125], v[214:217], v[24:27]
	v_mfma_f32_16x16x32_bf16 v[24:27], v[130:133], v[214:217], v[28:31]
	v_mfma_f32_16x16x32_bf16 v[28:31], v[164:167], v[214:217], v[102:105]
	v_mfma_f32_16x16x32_bf16 v[102:105], v[168:171], v[214:217], v[106:109]
	v_mfma_f32_16x16x32_bf16 v[106:109], v[172:175], v[214:217], v[110:113]
	v_mfma_f32_16x16x32_bf16 v[110:113], v[176:179], v[214:217], v[114:117]
	v_mfma_f32_16x16x32_bf16 v[4:7], v[180:183], v[214:217], v[8:11]
	s_waitcnt vmcnt(8) lgkmcnt(11)
	v_mfma_f32_16x16x32_bf16 v[8:11], v[12:15], v[210:213], v[16:19]
	s_waitcnt lgkmcnt(10)
	v_mfma_f32_16x16x32_bf16 v[12:15], v[118:121], v[210:213], v[20:23]
	s_waitcnt lgkmcnt(9)
	v_mfma_f32_16x16x32_bf16 v[16:19], v[126:129], v[210:213], v[24:27]
	s_waitcnt lgkmcnt(8)
	v_mfma_f32_16x16x32_bf16 v[20:23], v[134:137], v[210:213], v[28:31]
	s_waitcnt lgkmcnt(3)
	v_mfma_f32_16x16x32_bf16 v[24:27], v[138:141], v[210:213], v[102:105]
	s_waitcnt lgkmcnt(2)
	v_mfma_f32_16x16x32_bf16 v[28:31], v[142:145], v[210:213], v[106:109]
	s_waitcnt lgkmcnt(1)
	v_mfma_f32_16x16x32_bf16 v[102:105], v[146:149], v[210:213], v[110:113]
	s_waitcnt lgkmcnt(0)
	v_mfma_f32_16x16x32_bf16 v[0:3], v[156:159], v[210:213], v[4:7]
	s_nop 2
	v_mov_b64_e32 v[4:5], s[38:39]
	v_mad_u64_u32 v[4:5], s[10:11], v72, s34, v[4:5]
	v_pk_mul_f32 v[6:7], v[32:33], v[8:9]
	s_waitcnt vmcnt(7)
	v_lshlrev_b32_e32 v8, 16, v88
	v_and_b32_e32 v9, 0xffff0000, v88
	v_mad_i32_i24 v5, v73, s34, v5
	v_pk_mul_f32 v[6:7], v[6:7], v[8:9]
	v_pk_mul_f32 v[8:9], v[32:33], v[10:11]
	v_lshlrev_b32_e32 v10, 16, v89
	v_and_b32_e32 v11, 0xffff0000, v89
	v_lshl_add_u64 v[4:5], v[4:5], 0, s[8:9]
	v_pk_mul_f32 v[8:9], v[8:9], v[10:11]
	v_lshl_add_u64 v[4:5], v[4:5], 0, v[70:71]
	v_cvt_pk_bf16_f32 v6, v6, v7
	v_cvt_pk_bf16_f32 v7, v8, v9
	global_store_dwordx2 v[4:5], v[6:7], off offset:2048
	v_pk_mul_f32 v[6:7], v[32:33], v[12:13]
	s_waitcnt vmcnt(7)
	v_lshlrev_b32_e32 v8, 16, v86
	v_and_b32_e32 v9, 0xffff0000, v86
	v_pk_mul_f32 v[6:7], v[6:7], v[8:9]
	v_pk_mul_f32 v[8:9], v[32:33], v[14:15]
	v_lshlrev_b32_e32 v10, 16, v87
	v_and_b32_e32 v11, 0xffff0000, v87
	v_pk_mul_f32 v[8:9], v[8:9], v[10:11]
	v_cvt_pk_bf16_f32 v6, v6, v7
	v_cvt_pk_bf16_f32 v7, v8, v9
	global_store_dwordx2 v[4:5], v[6:7], off offset:2080
	v_pk_mul_f32 v[6:7], v[32:33], v[16:17]
	s_waitcnt vmcnt(7)
	v_lshlrev_b32_e32 v8, 16, v84
	v_and_b32_e32 v9, 0xffff0000, v84
	v_pk_mul_f32 v[6:7], v[6:7], v[8:9]
	v_pk_mul_f32 v[8:9], v[32:33], v[18:19]
	v_lshlrev_b32_e32 v10, 16, v85
	v_and_b32_e32 v11, 0xffff0000, v85
	v_pk_mul_f32 v[8:9], v[8:9], v[10:11]
	v_cvt_pk_bf16_f32 v6, v6, v7
	v_cvt_pk_bf16_f32 v7, v8, v9
	global_store_dwordx2 v[4:5], v[6:7], off offset:2112
	v_pk_mul_f32 v[6:7], v[32:33], v[20:21]
	s_waitcnt vmcnt(7)
	v_lshlrev_b32_e32 v8, 16, v82
	v_and_b32_e32 v9, 0xffff0000, v82
	v_pk_mul_f32 v[6:7], v[6:7], v[8:9]
	v_pk_mul_f32 v[8:9], v[32:33], v[22:23]
	v_lshlrev_b32_e32 v10, 16, v83
	v_and_b32_e32 v11, 0xffff0000, v83
	v_pk_mul_f32 v[8:9], v[8:9], v[10:11]
	v_cvt_pk_bf16_f32 v6, v6, v7
	v_cvt_pk_bf16_f32 v7, v8, v9
	global_store_dwordx2 v[4:5], v[6:7], off offset:2144
	v_pk_mul_f32 v[6:7], v[32:33], v[24:25]
	s_waitcnt vmcnt(7)
	v_lshlrev_b32_e32 v8, 16, v80
	v_and_b32_e32 v9, 0xffff0000, v80
	v_pk_mul_f32 v[6:7], v[6:7], v[8:9]
	v_pk_mul_f32 v[8:9], v[32:33], v[26:27]
	v_lshlrev_b32_e32 v10, 16, v81
	v_and_b32_e32 v11, 0xffff0000, v81
	v_pk_mul_f32 v[8:9], v[8:9], v[10:11]
	v_cvt_pk_bf16_f32 v6, v6, v7
	v_cvt_pk_bf16_f32 v7, v8, v9
	global_store_dwordx2 v[4:5], v[6:7], off offset:2176
	v_pk_mul_f32 v[6:7], v[32:33], v[28:29]
	s_waitcnt vmcnt(7)
	v_lshlrev_b32_e32 v8, 16, v78
	v_and_b32_e32 v9, 0xffff0000, v78
	v_pk_mul_f32 v[6:7], v[6:7], v[8:9]
	v_pk_mul_f32 v[8:9], v[32:33], v[30:31]
	v_lshlrev_b32_e32 v10, 16, v79
	v_and_b32_e32 v11, 0xffff0000, v79
	v_pk_mul_f32 v[8:9], v[8:9], v[10:11]
	v_cvt_pk_bf16_f32 v6, v6, v7
	v_cvt_pk_bf16_f32 v7, v8, v9
	global_store_dwordx2 v[4:5], v[6:7], off offset:2208
	v_pk_mul_f32 v[6:7], v[32:33], v[102:103]
	s_waitcnt vmcnt(7)
	v_lshlrev_b32_e32 v8, 16, v76
	v_and_b32_e32 v9, 0xffff0000, v76
	v_pk_mul_f32 v[6:7], v[6:7], v[8:9]
	v_pk_mul_f32 v[8:9], v[32:33], v[104:105]
	v_lshlrev_b32_e32 v10, 16, v77
	v_and_b32_e32 v11, 0xffff0000, v77
	v_pk_mul_f32 v[8:9], v[8:9], v[10:11]
	v_cvt_pk_bf16_f32 v6, v6, v7
	v_cvt_pk_bf16_f32 v7, v8, v9
	global_store_dwordx2 v[4:5], v[6:7], off offset:2240
	v_pk_mul_f32 v[0:1], v[32:33], v[0:1]
	s_waitcnt vmcnt(7)
	v_lshlrev_b32_e32 v6, 16, v74
	v_and_b32_e32 v7, 0xffff0000, v74
	v_pk_mul_f32 v[0:1], v[0:1], v[6:7]
	v_pk_mul_f32 v[2:3], v[32:33], v[2:3]
	v_lshlrev_b32_e32 v6, 16, v75
	v_and_b32_e32 v7, 0xffff0000, v75
	v_pk_mul_f32 v[2:3], v[2:3], v[6:7]
	s_add_i32 s22, s22, s94
	s_add_i32 s18, s18, s29
	v_cvt_pk_bf16_f32 v0, v0, v1
	v_cvt_pk_bf16_f32 v1, v2, v3
	s_cmpk_gt_i32 s22, 0x3ff
	global_store_dwordx2 v[4:5], v[0:1], off offset:2272
	s_barrier
	s_cbranch_scc0 .LBB0_117
